# P4 selected branch: per-visit entry() replaced by wave-uniform SALU arithmetic + v_readlane from a VGPR copy of the selection list (no integer division, no LDS round trip)
# speedup vs baseline: 1.0505x; 1.0160x over previous
.LBB0_569:
	s_or_b64 exec, exec, s[12:13]
	v_min_i32_e32 v153, 2, v229
	v_sub_u32_e32 v154, 15, v153
	v_lshlrev_b32_e32 v1, 1, v154
	v_add_u32_e32 v155, v1, v153
	s_waitcnt vmcnt(0)
	v_pk_mul_f32 v[14:15], v[2:3], v[14:15] op_sel_hi:[0,1]
	v_pk_mul_f32 v[12:13], v[2:3], v[12:13] op_sel_hi:[0,1]
	v_pk_mul_f32 v[48:49], v[2:3], v[26:27] op_sel_hi:[0,1]
	v_pk_mul_f32 v[28:29], v[2:3], v[24:25] op_sel_hi:[0,1]
	v_pk_mul_f32 v[26:27], v[2:3], v[22:23] op_sel_hi:[0,1]
	v_pk_mul_f32 v[52:53], v[2:3], v[20:21] op_sel_hi:[0,1]
	v_pk_mul_f32 v[24:25], v[2:3], v[18:19] op_sel_hi:[0,1]
	v_pk_mul_f32 v[50:51], v[2:3], v[16:17] op_sel_hi:[0,1]
	v_min_i32_e32 v2, 0, v155
	v_cmp_ge_i32_e32 vcc, v229, v2
	ds_write2st64_b32 v213, v12, v13 offset1:1
	ds_write2st64_b32 v213, v14, v15 offset0:2 offset1:3
	ds_write2st64_b32 v213, v28, v29 offset0:4 offset1:5
	ds_write2st64_b32 v213, v48, v49 offset0:6 offset1:7
	ds_write2st64_b32 v213, v52, v53 offset0:8 offset1:9
	ds_write2st64_b32 v213, v26, v27 offset0:10 offset1:11
	ds_write2st64_b32 v213, v50, v51 offset0:12 offset1:13
	ds_write2st64_b32 v213, v24, v25 offset0:14 offset1:15
	v_lshl_add_u32 v253, v207, 2, v210
	ds_read_b32 v252, v253 offset:5120
	v_readfirstlane_b32 s75, v229
	v_add_u32_e32 v230, 1, v153
	v_mov_b32_e32 v236, -1
	v_sub_u32_e32 v44, 0, v154
	v_mov_b32_e32 v235, 0
	v_mov_b32_e32 v234, 0
	s_min_i32 s32, s75, 2
	s_sub_i32 s36, 15, s32
	s_lshl_b32 s37, s36, 1
	s_add_i32 s37, s37, s32
	s_waitcnt lgkmcnt(0)
	v_mov_b32_e32 v2, v0
	v_mov_b32_e32 v3, v0
	v_add_u32_e32 v231, v1, v230
	v_mov_b32_e32 v1, v0
	v_mov_b64_e32 v[30:31], v[2:3]
	v_mov_b64_e32 v[34:35], v[2:3]
	v_mov_b64_e32 v[38:39], v[2:3]
	v_mov_b64_e32 v[42:43], v[2:3]
	v_cmp_lt_i32_e32 vcc, 0, v231
	v_mov_b32_e32 v237, 0
	v_mov_b64_e32 v[28:29], v[0:1]
	v_mov_b64_e32 v[32:33], v[0:1]
	v_mov_b64_e32 v[36:37], v[0:1]
	v_mov_b64_e32 v[40:41], v[0:1]
	s_and_saveexec_b64 s[16:17], vcc
	s_cbranch_execz .LBB0_607
	v_lshlrev_b32_e32 v2, 12, v235
	v_ashrrev_i32_e32 v3, 31, v2
	v_lshl_add_u64 v[12:13], v[198:199], 0, v[2:3]
	v_lshl_add_u64 v[2:3], v[200:201], 0, v[2:3]
	global_load_dwordx4 v[52:55], v[12:13], off offset:3072
	global_load_dwordx4 v[56:59], v[12:13], off offset:2048
	global_load_dwordx4 v[60:63], v[12:13], off offset:1024
	global_load_dwordx4 v[64:67], v[12:13], off
	global_load_dwordx4 v[84:87], v[2:3], off offset:3072
	global_load_dwordx4 v[88:91], v[2:3], off offset:2048
	global_load_dwordx4 v[92:95], v[2:3], off offset:1024
	global_load_dwordx4 v[96:99], v[2:3], off
	v_lshlrev_b32_e32 v2, 12, v234
	v_ashrrev_i32_e32 v3, 31, v2
	v_lshl_add_u64 v[24:25], v[198:199], 0, v[2:3]
	v_lshl_add_u64 v[2:3], v[200:201], 0, v[2:3]
	global_load_dwordx4 v[12:15], v[24:25], off offset:3072
	global_load_dwordx4 v[16:19], v[24:25], off offset:2048
	global_load_dwordx4 v[20:23], v[24:25], off offset:1024
	s_nop 0
	global_load_dwordx4 v[24:27], v[24:25], off
	s_nop 0
	global_load_dwordx4 v[68:71], v[2:3], off offset:3072
	global_load_dwordx4 v[72:75], v[2:3], off offset:2048
	global_load_dwordx4 v[76:79], v[2:3], off offset:1024
	global_load_dwordx4 v[80:83], v[2:3], off
	v_lshlrev_b32_e32 v1, 16, v8
	v_and_b32_e32 v2, 0xffff0000, v8
	v_mul_f32_e32 v1, 0x41000000, v1
	v_mul_f32_e32 v2, 0x41000000, v2
	v_mov_b32_e32 v150, v0
	v_cvt_pk_fp8_f32 v150, v1, v2
	v_lshlrev_b32_e32 v3, 16, v9
	v_and_b32_e32 v2, 0xffff0000, v9
	v_mul_f32_e32 v1, 0x41000000, v3
	v_mul_f32_e32 v2, 0x41000000, v2
	v_cvt_pk_fp8_f32 v150, v1, v2 op_sel:[0,0,1]
	v_lshlrev_b32_e32 v1, 16, v10
	v_and_b32_e32 v2, 0xffff0000, v10
	v_mul_f32_e32 v1, 0x41000000, v1
	v_mul_f32_e32 v2, 0x41000000, v2
	v_mov_b32_e32 v151, v0
	v_cvt_pk_fp8_f32 v151, v1, v2
	v_lshlrev_b32_e32 v3, 16, v11
	v_and_b32_e32 v2, 0xffff0000, v11
	v_mul_f32_e32 v1, 0x41000000, v3
	v_mul_f32_e32 v2, 0x41000000, v2
	v_cvt_pk_fp8_f32 v151, v1, v2 op_sel:[0,0,1]
	v_lshlrev_b32_e32 v1, 16, v4
	v_and_b32_e32 v2, 0xffff0000, v4
	v_mul_f32_e32 v1, 0x41000000, v1
	v_mul_f32_e32 v2, 0x41000000, v2
	v_mov_b32_e32 v10, v0
	v_cvt_pk_fp8_f32 v10, v1, v2
	v_max_i32_e32 v232, v154, v44
	v_lshlrev_b32_e32 v3, 16, v5
	v_and_b32_e32 v2, 0xffff0000, v5
	v_cvt_f32_u32_e32 v4, v232
	v_mul_f32_e32 v1, 0x41000000, v3
	v_mul_f32_e32 v2, 0x41000000, v2
	v_cvt_pk_fp8_f32 v10, v1, v2 op_sel:[0,0,1]
	v_lshlrev_b32_e32 v1, 16, v6
	v_and_b32_e32 v2, 0xffff0000, v6
	v_mul_f32_e32 v1, 0x41000000, v1
	v_mul_f32_e32 v2, 0x41000000, v2
	v_mov_b32_e32 v11, v0
	v_cvt_pk_fp8_f32 v11, v1, v2
	v_rcp_iflag_f32_e32 v1, v4
	v_lshlrev_b32_e32 v3, 16, v7
	v_and_b32_e32 v2, 0xffff0000, v7
	v_mul_f32_e32 v3, 0x41000000, v3
	v_mul_f32_e32 v1, 0x4f7ffffe, v1
	v_cvt_u32_f32_e32 v1, v1
	v_mul_f32_e32 v2, 0x41000000, v2
	v_cvt_pk_fp8_f32 v11, v3, v2 op_sel:[0,0,1]
	v_sub_u32_e32 v2, 0, v232
	v_mul_lo_u32 v2, v2, v1
	v_mul_hi_u32 v2, v1, v2
	v_add_u32_e32 v152, v1, v2
	v_mov_b32_e32 v2, v0
	v_mov_b32_e32 v3, v0
	v_mov_b32_e32 v1, v0
	v_mov_b64_e32 v[42:43], v[2:3]
	v_mov_b64_e32 v[38:39], v[2:3]
	v_mov_b64_e32 v[34:35], v[2:3]
	v_mov_b64_e32 v[30:31], v[2:3]
	v_cmp_eq_u32_e32 vcc, 0, v155
	v_ashrrev_i32_e32 v233, 31, v154
	s_mov_b32 s72, 0
	v_mov_b32_e32 v238, 0xf149f2ca
	v_mov_b32_e32 v241, 0
	s_mov_b64 s[18:19], 0
	v_mov_b64_e32 v[40:41], v[0:1]
	v_mov_b64_e32 v[36:37], v[0:1]
	v_mov_b64_e32 v[32:33], v[0:1]
	v_mov_b64_e32 v[28:29], v[0:1]
	s_branch .LBB0_578

.LBB0_578:
	s_add_i32 s24, s72, 1
	s_waitcnt vmcnt(24)
	s_min_i32 s93, s24, s37
	s_cmp_le_i32 s93, s32
	s_cbranch_scc0 .Lsel_pair_1
	s_sub_i32 s94, s75, 1
	s_cmp_eq_u32 s93, s32
	s_cselect_b32 s94, s75, s94
	s_mov_b32 s98, s94
	s_mov_b32 s100, -1
	s_branch .Lsel_done_1
.Lsel_pair_1:
	s_sub_i32 s93, s93, s32
	s_sub_i32 s93, s93, 1
	s_cmp_ge_i32 s93, s36
	s_cselect_b32 s100, 1, 0
	s_cselect_b32 s101, s36, 0
	s_sub_i32 s93, s93, s101
	s_lshl_b32 s101, s100, 5
	s_add_i32 s101, s101, s93
	s_nop 0
	v_readlane_b32 s94, v252, s101
	s_add_i32 s101, s101, 16
	s_nop 0
	v_readlane_b32 s98, v252, s101
.Lsel_done_1:
	v_mov_b32_e32 v240, s100
	s_nop 1
	v_mov_b32_e32 v1, s94
	v_mov_b32_e32 v239, s98
	v_lshlrev_b32_e32 v2, 12, v1
	s_waitcnt vmcnt(16)
	v_lshlrev_b32_e32 v100, 12, v239
	v_ashrrev_i32_e32 v3, 31, v2
	v_ashrrev_i32_e32 v101, 31, v100
	v_lshl_add_u64 v[4:5], v[200:201], 0, v[2:3]
	v_lshl_add_u64 v[2:3], v[198:199], 0, v[2:3]
	v_lshl_add_u64 v[102:103], v[200:201], 0, v[100:101]
	v_lshl_add_u64 v[100:101], v[198:199], 0, v[100:101]
	global_load_dwordx4 v[128:131], v[4:5], off
	global_load_dwordx4 v[124:127], v[4:5], off offset:1024
	global_load_dwordx4 v[120:123], v[4:5], off offset:2048
	global_load_dwordx4 v[116:119], v[4:5], off offset:3072
	global_load_dwordx4 v[48:51], v[2:3], off
	global_load_dwordx4 v[44:47], v[2:3], off offset:1024
	global_load_dwordx4 v[6:9], v[2:3], off offset:2048
	s_nop 0
	global_load_dwordx4 v[2:5], v[2:3], off offset:3072
	s_nop 0
	global_load_dwordx4 v[144:147], v[102:103], off
	global_load_dwordx4 v[140:143], v[102:103], off offset:1024
	global_load_dwordx4 v[136:139], v[102:103], off offset:2048
	global_load_dwordx4 v[132:135], v[102:103], off offset:3072
	global_load_dwordx4 v[112:115], v[100:101], off
	global_load_dwordx4 v[108:111], v[100:101], off offset:1024
	global_load_dwordx4 v[104:107], v[100:101], off offset:2048
	s_nop 0
	global_load_dwordx4 v[100:103], v[100:101], off offset:3072
	v_cmp_lt_i32_e64 s[0:1], -1, v236
	s_and_saveexec_b64 s[12:13], s[0:1]
	s_xor_b64 s[20:21], exec, s[12:13]
	s_cbranch_execz .LBB0_586
	v_lshlrev_b32_e32 v236, 1, v236
	v_cmp_ne_u32_e64 s[12:13], v208, v236
	v_cmp_ge_i32_e64 s[14:15], v234, v229
	v_cmp_eq_u32_e64 s[0:1], v208, v236
	s_or_b64 s[12:13], s[12:13], s[14:15]
	s_mov_b64 s[14:15], -1
	s_and_saveexec_b64 s[22:23], s[12:13]
	v_or_b32_e32 v234, 1, v236
	v_cmp_eq_u32_e64 s[12:13], v208, v234
	v_cmp_lt_i32_e64 s[14:15], v235, v229
	s_and_b64 s[12:13], s[12:13], s[14:15]
	s_orn2_b64 s[14:15], s[12:13], exec
	s_or_b64 exec, exec, s[22:23]
	v_cndmask_b32_e64 v243, 0, v151, s[0:1]
	v_cndmask_b32_e64 v242, 0, v150, s[0:1]
	v_cndmask_b32_e64 v245, 0, v11, s[0:1]
	v_cndmask_b32_e64 v244, 0, v10, s[0:1]
	s_waitcnt vmcnt(16)
	v_mfma_f32_16x16x32_fp8_fp8 v[234:237], v[80:81], v[242:243], 0
	s_and_b64 s[12:13], s[0:1], s[14:15]
	v_mfma_f32_16x16x32_fp8_fp8 v[80:83], v[82:83], v[244:245], v[234:237]
	s_nop 5
	v_cndmask_b32_e64 v235, v151, 0, s[0:1]
	v_cndmask_b32_e64 v234, v150, 0, s[0:1]
	v_cndmask_b32_e64 v237, v11, 0, s[0:1]
	v_cndmask_b32_e64 v236, v10, 0, s[0:1]
	v_mfma_f32_16x16x32_fp8_fp8 v[80:83], v[96:97], v[234:235], v[80:83]
	s_xor_b64 s[0:1], s[0:1], -1
	s_and_b64 s[0:1], s[14:15], s[0:1]
	v_mfma_f32_16x16x32_fp8_fp8 v[80:83], v[98:99], v[236:237], v[80:83]
	v_mfma_f32_16x16x32_fp8_fp8 v[96:99], v[76:77], v[242:243], 0
	v_mfma_f32_16x16x32_fp8_fp8 v[76:79], v[78:79], v[244:245], v[96:99]
	s_nop 5
	v_mul_f32_e64 v82, v82, s76
	v_mul_f32_e64 v83, v83, s76
	v_pk_mul_f32 v[80:81], v[80:81], s[76:77] op_sel_hi:[1,0]
	v_mfma_f32_16x16x32_fp8_fp8 v[76:79], v[92:93], v[234:235], v[76:79]
	v_mfma_f32_16x16x32_fp8_fp8 v[76:79], v[94:95], v[236:237], v[76:79]
	v_mfma_f32_16x16x32_fp8_fp8 v[92:95], v[72:73], v[242:243], 0
	v_mfma_f32_16x16x32_fp8_fp8 v[72:75], v[74:75], v[244:245], v[92:95]
	s_nop 5
	v_mul_f32_e64 v78, v78, s76
	v_mul_f32_e64 v79, v79, s76
	v_pk_mul_f32 v[76:77], v[76:77], s[76:77] op_sel_hi:[1,0]
	v_mfma_f32_16x16x32_fp8_fp8 v[72:75], v[88:89], v[234:235], v[72:75]
	v_mfma_f32_16x16x32_fp8_fp8 v[72:75], v[90:91], v[236:237], v[72:75]
	v_mfma_f32_16x16x32_fp8_fp8 v[88:91], v[68:69], v[242:243], 0
	v_mfma_f32_16x16x32_fp8_fp8 v[68:71], v[70:71], v[244:245], v[88:91]
	s_nop 5
	v_mul_f32_e64 v74, v74, s76
	v_mul_f32_e64 v75, v75, s76
	v_pk_mul_f32 v[72:73], v[72:73], s[76:77] op_sel_hi:[1,0]
	v_mfma_f32_16x16x32_fp8_fp8 v[68:71], v[84:85], v[234:235], v[68:71]
	v_max_f32_e32 v84, v80, v81
	v_max_f32_e32 v85, v82, v83
	v_mov_b32_e32 v89, 0
	v_mfma_f32_16x16x32_fp8_fp8 v[68:71], v[86:87], v[236:237], v[68:71]
	v_max_f32_e32 v86, v78, v79
	v_max3_f32 v86, v76, v77, v86
	v_max3_f32 v84, v84, v85, v86
	v_max_f32_e32 v85, v74, v75
	v_max3_f32 v85, v72, v73, v85
	s_nop 2
	v_pk_mul_f32 v[70:71], v[70:71], s[76:77] op_sel_hi:[1,0]
	v_pk_mul_f32 v[68:69], v[68:69], s[76:77] op_sel_hi:[1,0]
	v_max_f32_e32 v86, v70, v71
	v_max3_f32 v86, v68, v69, v86
	v_max3_f32 v84, v84, v85, v86
	ds_bpermute_b32 v85, v223, v84
	v_mov_b32_e32 v90, 0
	s_waitcnt lgkmcnt(0)
	v_max_f32_e32 v85, v85, v85
	v_max_f32_e32 v84, v84, v85
	ds_bpermute_b32 v85, v224, v84
	s_waitcnt lgkmcnt(0)
	v_max3_f32 v84, v238, v84, v85
	v_cndmask_b32_e64 v85, v238, v84, s[14:15]
	v_sub_f32_e32 v88, 0x41000000, v85
	v_add_f32_e32 v80, v80, v88
	v_add_f32_e32 v81, v81, v88
	v_add_f32_e32 v76, v76, v88
	v_add_f32_e32 v77, v77, v88
	v_exp_f32_e32 v80, v80
	v_exp_f32_e32 v81, v81
	v_exp_f32_e32 v76, v76
	v_exp_f32_e32 v77, v77
	v_add_f32_e32 v82, v82, v88
	v_add_f32_e32 v83, v83, v88
	v_add_f32_e32 v78, v78, v88
	v_add_f32_e32 v79, v79, v88
	v_exp_f32_e32 v82, v82
	v_exp_f32_e32 v83, v83
	v_exp_f32_e32 v78, v78
	v_exp_f32_e32 v79, v79
	v_cvt_pk_fp8_f32 v90, v76, v77
	v_cvt_pk_fp8_f32 v89, v80, v81
	v_sub_f32_e32 v84, v238, v85
	v_exp_f32_e32 v84, v84
	v_cvt_pk_fp8_f32 v90, v78, v79 op_sel:[0,0,1]
	v_cvt_pk_fp8_f32 v89, v82, v83 op_sel:[0,0,1]
	v_add_f32_e32 v72, v72, v88
	v_pk_mul_f32 v[42:43], v[42:43], v[84:85] op_sel_hi:[1,0]
	v_pk_mul_f32 v[40:41], v[40:41], v[84:85] op_sel_hi:[1,0]
	v_cndmask_b32_e64 v87, 0, v90, s[12:13]
	v_cndmask_b32_e64 v86, 0, v89, s[12:13]
	v_pk_mul_f32 v[38:39], v[38:39], v[84:85] op_sel_hi:[1,0]
	v_pk_mul_f32 v[36:37], v[36:37], v[84:85] op_sel_hi:[1,0]
	v_pk_mul_f32 v[34:35], v[34:35], v[84:85] op_sel_hi:[1,0]
	v_pk_mul_f32 v[32:33], v[32:33], v[84:85] op_sel_hi:[1,0]
	v_add_f32_e32 v73, v73, v88
	v_mfma_f32_16x16x32_fp8_fp8 v[40:43], v[24:25], v[86:87], v[40:43]
	v_add_f32_e32 v24, v68, v88
	v_exp_f32_e32 v72, v72
	v_exp_f32_e32 v73, v73
	v_mfma_f32_16x16x32_fp8_fp8 v[36:39], v[20:21], v[86:87], v[36:39]
	v_exp_f32_e32 v68, v24
	v_pk_mul_f32 v[30:31], v[30:31], v[84:85] op_sel_hi:[1,0]
	v_pk_mul_f32 v[28:29], v[28:29], v[84:85] op_sel_hi:[1,0]
	v_mfma_f32_16x16x32_fp8_fp8 v[32:35], v[16:17], v[86:87], v[32:35]
	v_add_f32_e32 v16, v69, v88
	v_exp_f32_e32 v69, v16
	v_add_f32_e32 v16, v70, v88
	v_mfma_f32_16x16x32_fp8_fp8 v[28:31], v[12:13], v[86:87], v[28:31]
	v_cndmask_b32_e64 v13, 0, v90, s[0:1]
	v_cndmask_b32_e64 v12, 0, v89, s[0:1]
	v_add_f32_e32 v74, v74, v88
	v_add_f32_e32 v75, v75, v88
	v_mfma_f32_16x16x32_fp8_fp8 v[36:39], v[60:61], v[12:13], v[36:39]
	v_exp_f32_e32 v60, v16
	v_add_f32_e32 v16, v71, v88
	v_exp_f32_e32 v74, v74
	v_mfma_f32_16x16x32_fp8_fp8 v[32:35], v[56:57], v[12:13], v[32:35]
	v_mov_b32_e32 v56, 0
	v_mov_b32_e32 v57, 0
	v_exp_f32_e32 v75, v75
	v_exp_f32_e32 v61, v16
	v_cvt_pk_fp8_f32 v57, v68, v69
	v_cvt_pk_fp8_f32 v56, v72, v73
	v_mfma_f32_16x16x32_fp8_fp8 v[40:43], v[64:65], v[12:13], v[40:43]
	v_mov_b32_e32 v238, v85
	v_cvt_pk_fp8_f32 v57, v60, v61 op_sel:[0,0,1]
	v_cvt_pk_fp8_f32 v56, v74, v75 op_sel:[0,0,1]
	v_mfma_f32_16x16x32_fp8_fp8 v[28:31], v[52:53], v[12:13], v[28:31]
	v_cndmask_b32_e64 v13, 0, v57, s[12:13]
	v_cndmask_b32_e64 v12, 0, v56, s[12:13]
	s_nop 1
	v_mfma_f32_16x16x32_fp8_fp8 v[24:27], v[26:27], v[12:13], v[40:43]
	v_mfma_f32_16x16x32_fp8_fp8 v[20:23], v[22:23], v[12:13], v[36:39]
	s_nop 2
	v_add_f32_e64 v36, v80, 0
	v_add_f32_e64 v37, v81, 0
	v_mfma_f32_16x16x32_fp8_fp8 v[16:19], v[18:19], v[12:13], v[32:35]
	s_nop 2
	v_add_f32_e64 v32, v82, 0
	v_add_f32_e64 v33, v83, 0
	v_pk_add_f32 v[34:35], v[76:77], v[36:37]
	v_pk_add_f32 v[32:33], v[78:79], v[32:33]
	v_mfma_f32_16x16x32_fp8_fp8 v[12:15], v[14:15], v[12:13], v[28:31]
	s_nop 2
	v_cndmask_b32_e64 v31, 0, v57, s[0:1]
	v_cndmask_b32_e64 v30, 0, v56, s[0:1]
	v_pk_add_f32 v[28:29], v[72:73], v[34:35]
	s_nop 0
	v_mfma_f32_16x16x32_fp8_fp8 v[40:43], v[66:67], v[30:31], v[24:27]
	s_nop 2
	v_add_f32_e64 v24, v74, v32
	v_add_f32_e64 v25, v75, v33
	v_pk_add_f32 v[26:27], v[68:69], v[28:29]
	v_pk_add_f32 v[24:25], v[60:61], v[24:25]
	v_mfma_f32_16x16x32_fp8_fp8 v[36:39], v[62:63], v[30:31], v[20:23]
	v_mfma_f32_16x16x32_fp8_fp8 v[32:35], v[58:59], v[30:31], v[16:19]
	s_nop 1
	v_pk_mov_b32 v[20:21], v[26:27], v[24:25] op_sel:[1,0]
	v_mov_b32_e32 v27, v25
	v_pk_add_f32 v[20:21], v[20:21], v[26:27]
	v_mfma_f32_16x16x32_fp8_fp8 v[28:31], v[54:55], v[30:31], v[12:15]
	v_add_f32_e32 v16, v20, v21
	v_cndmask_b32_e64 v237, 0, v16, s[14:15]
	v_fmac_f32_e32 v237, v241, v84

.LBB0_592:
	s_or_b64 exec, exec, s[12:13]
	s_add_i32 s72, s72, 2
	s_waitcnt vmcnt(23)
	s_min_i32 s93, s72, s37
	s_cmp_le_i32 s93, s32
	s_cbranch_scc0 .Lsel_pair_2
	s_sub_i32 s94, s75, 1
	s_cmp_eq_u32 s93, s32
	s_cselect_b32 s94, s75, s94
	s_mov_b32 s98, s94
	s_mov_b32 s100, -1
	s_branch .Lsel_done_2

.Lsel_done_2:
	v_mov_b32_e32 v236, s100
	s_nop 1
	v_mov_b32_e32 v234, s94
	v_mov_b32_e32 v235, s98
	v_lshlrev_b32_e32 v12, 12, v234
	s_waitcnt vmcnt(16)
	v_lshlrev_b32_e32 v52, 12, v235
	v_ashrrev_i32_e32 v13, 31, v12
	v_ashrrev_i32_e32 v53, 31, v52
	v_lshl_add_u64 v[14:15], v[200:201], 0, v[12:13]
	v_lshl_add_u64 v[12:13], v[198:199], 0, v[12:13]
	v_lshl_add_u64 v[54:55], v[200:201], 0, v[52:53]
	v_lshl_add_u64 v[52:53], v[198:199], 0, v[52:53]
	global_load_dwordx4 v[80:83], v[14:15], off
	global_load_dwordx4 v[76:79], v[14:15], off offset:1024
	global_load_dwordx4 v[72:75], v[14:15], off offset:2048
	global_load_dwordx4 v[68:71], v[14:15], off offset:3072
	global_load_dwordx4 v[24:27], v[12:13], off
	global_load_dwordx4 v[20:23], v[12:13], off offset:1024
	global_load_dwordx4 v[16:19], v[12:13], off offset:2048
	s_nop 0
	global_load_dwordx4 v[12:15], v[12:13], off offset:3072
	s_nop 0
	global_load_dwordx4 v[96:99], v[54:55], off
	global_load_dwordx4 v[92:95], v[54:55], off offset:1024
	global_load_dwordx4 v[88:91], v[54:55], off offset:2048
	global_load_dwordx4 v[84:87], v[54:55], off offset:3072
	global_load_dwordx4 v[64:67], v[52:53], off
	global_load_dwordx4 v[60:63], v[52:53], off offset:1024
	global_load_dwordx4 v[56:59], v[52:53], off offset:2048
	s_nop 0
	global_load_dwordx4 v[52:55], v[52:53], off offset:3072
	v_cmp_lt_u32_e64 s[0:1], s24, v231
	s_and_saveexec_b64 s[20:21], s[0:1]
	s_cbranch_execz .LBB0_577
	v_cmp_lt_i32_e64 s[0:1], -1, v240
	s_and_saveexec_b64 s[12:13], s[0:1]
	s_xor_b64 s[22:23], exec, s[12:13]
	s_cbranch_execz .LBB0_601
	v_lshlrev_b32_e32 v240, 1, v240
	v_cmp_ne_u32_e64 s[12:13], v208, v240
	v_cmp_ge_i32_e64 s[14:15], v1, v229
	v_cmp_eq_u32_e64 s[0:1], v208, v240
	s_or_b64 s[12:13], s[12:13], s[14:15]
	s_mov_b64 s[14:15], -1
	s_and_saveexec_b64 s[24:25], s[12:13]
	v_or_b32_e32 v1, 1, v240
	v_cmp_eq_u32_e64 s[12:13], v208, v1
	v_cmp_lt_i32_e64 s[14:15], v239, v229
	s_and_b64 s[12:13], s[12:13], s[14:15]
	s_orn2_b64 s[14:15], s[12:13], exec
	s_or_b64 exec, exec, s[24:25]
	v_cndmask_b32_e64 v245, 0, v151, s[0:1]
	v_cndmask_b32_e64 v244, 0, v150, s[0:1]
	v_cndmask_b32_e64 v247, 0, v11, s[0:1]
	v_cndmask_b32_e64 v246, 0, v10, s[0:1]
	s_waitcnt vmcnt(31)
	v_mfma_f32_16x16x32_fp8_fp8 v[240:243], v[128:129], v[244:245], 0
	s_and_b64 s[12:13], s[0:1], s[14:15]
	v_mfma_f32_16x16x32_fp8_fp8 v[128:131], v[130:131], v[246:247], v[240:243]
	s_nop 5
	v_cndmask_b32_e64 v241, v151, 0, s[0:1]
	v_cndmask_b32_e64 v240, v150, 0, s[0:1]
	v_cndmask_b32_e64 v243, v11, 0, s[0:1]
	v_cndmask_b32_e64 v242, v10, 0, s[0:1]
	s_waitcnt vmcnt(23)
	v_mfma_f32_16x16x32_fp8_fp8 v[128:131], v[144:145], v[240:241], v[128:131]
	s_xor_b64 s[0:1], s[0:1], -1
	s_and_b64 s[0:1], s[14:15], s[0:1]
	v_mfma_f32_16x16x32_fp8_fp8 v[128:131], v[146:147], v[242:243], v[128:131]
	v_mfma_f32_16x16x32_fp8_fp8 v[144:147], v[124:125], v[244:245], 0
	v_mfma_f32_16x16x32_fp8_fp8 v[124:127], v[126:127], v[246:247], v[144:147]
	s_nop 5
	v_mul_f32_e64 v130, v130, s76
	v_mul_f32_e64 v131, v131, s76
	v_pk_mul_f32 v[128:129], v[128:129], s[76:77] op_sel_hi:[1,0]
	s_waitcnt vmcnt(22)
	v_mfma_f32_16x16x32_fp8_fp8 v[124:127], v[140:141], v[240:241], v[124:127]
	v_max_f32_e32 v1, v128, v129
	v_mfma_f32_16x16x32_fp8_fp8 v[124:127], v[142:143], v[242:243], v[124:127]
	v_mfma_f32_16x16x32_fp8_fp8 v[140:143], v[120:121], v[244:245], 0
	v_mfma_f32_16x16x32_fp8_fp8 v[120:123], v[122:123], v[246:247], v[140:143]
	s_nop 5
	v_mul_f32_e64 v126, v126, s76
	v_mul_f32_e64 v127, v127, s76
	v_pk_mul_f32 v[124:125], v[124:125], s[76:77] op_sel_hi:[1,0]
	s_waitcnt vmcnt(21)
	v_mfma_f32_16x16x32_fp8_fp8 v[120:123], v[136:137], v[240:241], v[120:123]
	v_mfma_f32_16x16x32_fp8_fp8 v[120:123], v[138:139], v[242:243], v[120:123]
	v_mfma_f32_16x16x32_fp8_fp8 v[136:139], v[116:117], v[244:245], 0
	v_mfma_f32_16x16x32_fp8_fp8 v[116:119], v[118:119], v[246:247], v[136:139]
	s_nop 5
	v_mul_f32_e64 v122, v122, s76
	v_mul_f32_e64 v123, v123, s76
	v_pk_mul_f32 v[120:121], v[120:121], s[76:77] op_sel_hi:[1,0]
	s_waitcnt vmcnt(20)
	v_mfma_f32_16x16x32_fp8_fp8 v[116:119], v[132:133], v[240:241], v[116:119]
	v_max_f32_e32 v133, v126, v127
	v_max_f32_e32 v132, v130, v131
	v_max3_f32 v133, v124, v125, v133
	v_mfma_f32_16x16x32_fp8_fp8 v[116:119], v[134:135], v[242:243], v[116:119]
	v_max3_f32 v1, v1, v132, v133
	v_max_f32_e32 v132, v122, v123
	v_max3_f32 v132, v120, v121, v132
	v_mov_b32_e32 v136, 0
	s_nop 3
	v_pk_mul_f32 v[118:119], v[118:119], s[76:77] op_sel_hi:[1,0]
	v_pk_mul_f32 v[116:117], v[116:117], s[76:77] op_sel_hi:[1,0]
	v_max_f32_e32 v133, v118, v119
	v_max3_f32 v133, v116, v117, v133
	v_max3_f32 v1, v1, v132, v133
	ds_bpermute_b32 v132, v223, v1
	s_waitcnt lgkmcnt(0)
	v_max_f32_e32 v132, v132, v132
	v_max_f32_e32 v1, v1, v132
	ds_bpermute_b32 v132, v224, v1
	s_waitcnt lgkmcnt(0)
	v_max3_f32 v1, v238, v1, v132
	v_cndmask_b32_e64 v241, v238, v1, s[14:15]
	v_sub_f32_e32 v133, 0x41000000, v241
	v_add_f32_e32 v128, v128, v133
	v_add_f32_e32 v129, v129, v133
	v_add_f32_e32 v124, v124, v133
	v_add_f32_e32 v125, v125, v133
	v_exp_f32_e32 v128, v128
	v_exp_f32_e32 v129, v129
	v_exp_f32_e32 v124, v124
	v_exp_f32_e32 v125, v125
	v_sub_f32_e32 v1, v238, v241
	v_add_f32_e32 v130, v130, v133
	v_add_f32_e32 v131, v131, v133
	v_add_f32_e32 v126, v126, v133
	v_add_f32_e32 v127, v127, v133
	v_exp_f32_e32 v132, v1
	v_mov_b32_e32 v1, 0
	v_exp_f32_e32 v130, v130
	v_exp_f32_e32 v131, v131
	v_exp_f32_e32 v126, v126
	v_exp_f32_e32 v127, v127
	v_cvt_pk_fp8_f32 v136, v124, v125
	v_cvt_pk_fp8_f32 v1, v128, v129
	v_pk_mul_f32 v[42:43], v[42:43], v[132:133] op_sel_hi:[1,0]
	v_pk_mul_f32 v[40:41], v[40:41], v[132:133] op_sel_hi:[1,0]
	v_cvt_pk_fp8_f32 v136, v126, v127 op_sel:[0,0,1]
	v_cvt_pk_fp8_f32 v1, v130, v131 op_sel:[0,0,1]
	v_pk_mul_f32 v[34:35], v[34:35], v[132:133] op_sel_hi:[1,0]
	v_pk_mul_f32 v[32:33], v[32:33], v[132:133] op_sel_hi:[1,0]
	v_cndmask_b32_e64 v135, 0, v136, s[12:13]
	v_cndmask_b32_e64 v134, 0, v1, s[12:13]
	v_pk_mul_f32 v[30:31], v[30:31], v[132:133] op_sel_hi:[1,0]
	v_pk_mul_f32 v[28:29], v[28:29], v[132:133] op_sel_hi:[1,0]
	v_add_f32_e32 v120, v120, v133
	v_add_f32_e32 v121, v121, v133
	v_mfma_f32_16x16x32_fp8_fp8 v[40:43], v[48:49], v[134:135], v[40:43]
	v_add_f32_e32 v48, v116, v133
	v_pk_mul_f32 v[38:39], v[38:39], v[132:133] op_sel_hi:[1,0]
	v_pk_mul_f32 v[36:37], v[36:37], v[132:133] op_sel_hi:[1,0]
	v_mfma_f32_16x16x32_fp8_fp8 v[32:35], v[6:7], v[134:135], v[32:35]
	v_exp_f32_e32 v120, v120
	v_exp_f32_e32 v121, v121
	v_add_f32_e32 v122, v122, v133
	v_mfma_f32_16x16x32_fp8_fp8 v[28:31], v[2:3], v[134:135], v[28:31]
	v_cndmask_b32_e64 v2, 0, v1, s[0:1]
	v_add_f32_e32 v1, v117, v133
	v_cndmask_b32_e64 v3, 0, v136, s[0:1]
	v_mfma_f32_16x16x32_fp8_fp8 v[36:39], v[44:45], v[134:135], v[36:39]
	v_exp_f32_e32 v44, v48
	v_exp_f32_e32 v45, v1
	v_add_f32_e32 v1, v118, v133
	v_exp_f32_e32 v48, v1
	v_add_f32_e32 v1, v119, v133
	v_add_f32_e32 v123, v123, v133
	v_exp_f32_e32 v49, v1
	s_waitcnt vmcnt(17)
	v_mfma_f32_16x16x32_fp8_fp8 v[32:35], v[104:105], v[2:3], v[32:35]
	v_mov_b32_e32 v1, 0
	v_mov_b32_e32 v104, 0
	v_exp_f32_e32 v122, v122
	v_exp_f32_e32 v123, v123
	v_cvt_pk_fp8_f32 v104, v44, v45
	v_cvt_pk_fp8_f32 v1, v120, v121
	v_mfma_f32_16x16x32_fp8_fp8 v[36:39], v[108:109], v[2:3], v[36:39]
	v_cvt_pk_fp8_f32 v104, v48, v49 op_sel:[0,0,1]
	v_cvt_pk_fp8_f32 v1, v122, v123 op_sel:[0,0,1]
	v_mfma_f32_16x16x32_fp8_fp8 v[40:43], v[112:113], v[2:3], v[40:43]
	s_waitcnt vmcnt(16)
	v_mfma_f32_16x16x32_fp8_fp8 v[28:31], v[100:101], v[2:3], v[28:31]
	v_cndmask_b32_e64 v3, 0, v104, s[12:13]
	v_cndmask_b32_e64 v2, 0, v1, s[12:13]
	s_nop 1
	v_mfma_f32_16x16x32_fp8_fp8 v[36:39], v[46:47], v[2:3], v[36:39]
	v_add_f32_e64 v46, v128, 0
	v_add_f32_e64 v47, v129, 0
	v_mfma_f32_16x16x32_fp8_fp8 v[6:9], v[8:9], v[2:3], v[32:35]
	s_nop 2
	v_add_f32_e64 v32, v130, 0
	v_add_f32_e64 v33, v131, 0
	v_pk_add_f32 v[34:35], v[124:125], v[46:47]
	v_pk_add_f32 v[32:33], v[126:127], v[32:33]
	v_mfma_f32_16x16x32_fp8_fp8 v[40:43], v[50:51], v[2:3], v[40:43]
	v_add_f32_e64 v32, v122, v32
	v_add_f32_e64 v33, v123, v33
	v_mfma_f32_16x16x32_fp8_fp8 v[2:5], v[4:5], v[2:3], v[28:31]
	v_add_f32_e64 v32, v48, v32
	v_add_f32_e64 v33, v49, v33
	s_nop 0
	v_pk_add_f32 v[28:29], v[120:121], v[34:35]
	v_cndmask_b32_e64 v31, 0, v104, s[0:1]
	v_pk_add_f32 v[28:29], v[44:45], v[28:29]
	v_cndmask_b32_e64 v30, 0, v1, s[0:1]
	v_pk_mov_b32 v[34:35], v[28:29], v[32:33] op_sel:[1,0]
	v_mov_b32_e32 v29, v33
	v_pk_add_f32 v[28:29], v[34:35], v[28:29]
	v_mfma_f32_16x16x32_fp8_fp8 v[40:43], v[114:115], v[30:31], v[40:43]
	v_add_f32_e32 v1, v28, v29
	v_cndmask_b32_e64 v242, 0, v1, s[14:15]
	v_fmac_f32_e32 v242, v237, v132
	v_mfma_f32_16x16x32_fp8_fp8 v[36:39], v[110:111], v[30:31], v[36:39]
	v_mfma_f32_16x16x32_fp8_fp8 v[32:35], v[106:107], v[30:31], v[6:9]
	v_mfma_f32_16x16x32_fp8_fp8 v[28:31], v[102:103], v[30:31], v[2:5]

	.amdhsa_kernel _Z4mega6Params
		.amdhsa_group_segment_fixed_size 16
		.amdhsa_private_segment_fixed_size 0
		.amdhsa_kernarg_size 392
		.amdhsa_user_sgpr_count 2
		.amdhsa_user_sgpr_dispatch_ptr 0
		.amdhsa_user_sgpr_queue_ptr 0
		.amdhsa_user_sgpr_kernarg_segment_ptr 1
		.amdhsa_user_sgpr_dispatch_id 0
		.amdhsa_user_sgpr_kernarg_preload_length 0
		.amdhsa_user_sgpr_kernarg_preload_offset 0
		.amdhsa_user_sgpr_private_segment_size 0
		.amdhsa_uses_dynamic_stack 0
		.amdhsa_enable_private_segment 0
		.amdhsa_system_sgpr_workgroup_id_x 1
		.amdhsa_system_sgpr_workgroup_id_y 0
		.amdhsa_system_sgpr_workgroup_id_z 0
		.amdhsa_system_sgpr_workgroup_info 0
		.amdhsa_system_vgpr_workitem_id 2
		.amdhsa_next_free_vgpr 256
		.amdhsa_next_free_sgpr 102
		.amdhsa_accum_offset 256
		.amdhsa_reserve_vcc 1
		.amdhsa_float_round_mode_32 0
		.amdhsa_float_round_mode_16_64 0
		.amdhsa_float_denorm_mode_32 3
		.amdhsa_float_denorm_mode_16_64 3
		.amdhsa_dx10_clamp 1
		.amdhsa_ieee_mode 1
		.amdhsa_fp16_overflow 0
		.amdhsa_tg_split 0
		.amdhsa_exception_fp_ieee_invalid_op 0
		.amdhsa_exception_fp_denorm_src 0
		.amdhsa_exception_fp_ieee_div_zero 0
		.amdhsa_exception_fp_ieee_overflow 0
		.amdhsa_exception_fp_ieee_underflow 0
		.amdhsa_exception_fp_ieee_inexact 0
		.amdhsa_exception_int_div_zero 0
	.end_amdhsa_kernel

amdhsa.kernels:
  - .agpr_count:     0
    .args:
      - .offset:         0
        .size:           136
        .value_kind:     by_value
      - .offset:         136
        .size:           4
        .value_kind:     hidden_block_count_x
      - .offset:         140
        .size:           4
        .value_kind:     hidden_block_count_y
      - .offset:         144
        .size:           4
        .value_kind:     hidden_block_count_z
      - .offset:         148
        .size:           2
        .value_kind:     hidden_group_size_x
      - .offset:         150
        .size:           2
        .value_kind:     hidden_group_size_y
      - .offset:         152
        .size:           2
        .value_kind:     hidden_group_size_z
      - .offset:         154
        .size:           2
        .value_kind:     hidden_remainder_x
      - .offset:         156
        .size:           2
        .value_kind:     hidden_remainder_y
      - .offset:         158
        .size:           2
        .value_kind:     hidden_remainder_z
      - .offset:         176
        .size:           8
        .value_kind:     hidden_global_offset_x
      - .offset:         184
        .size:           8
        .value_kind:     hidden_global_offset_y
      - .offset:         192
        .size:           8
        .value_kind:     hidden_global_offset_z
      - .offset:         200
        .size:           2
        .value_kind:     hidden_grid_dims
      - .offset:         224
        .size:           8
        .value_kind:     hidden_multigrid_sync_arg
      - .offset:         256
        .size:           4
        .value_kind:     hidden_dynamic_lds_size
    .group_segment_fixed_size: 16
    .kernarg_segment_align: 8
    .kernarg_segment_size: 392
    .language:       OpenCL C
    .language_version:
      - 2
      - 0
    .max_flat_workgroup_size: 512
    .name:           _Z4mega6Params
    .private_segment_fixed_size: 0
    .sgpr_count:     108
    .sgpr_spill_count: 6
    .symbol:         _Z4mega6Params.kd
    .uniform_work_group_size: 1
    .uses_dynamic_stack: false
    .vgpr_count:     256
    .vgpr_spill_count: 0
    .wavefront_size: 64
